# attention: per-tile barrier right before the first P.V MFMA of sub-step 1 (after the first 8 exps and their converts)
# baseline (speedup 1.0000x reference)
; __device__ __forceinline__ unsigned pk2(float lo, float hi) { return pg8::cvt_pk_bf16(lo, hi); }
; #define MFMA32(a, b, c) __builtin_amdgcn_mfma_f32_32x32x16_bf16((a), (b), (c), 0, 0, 0)
; __device__ __forceinline__ void attn_phase(const Args& a, int l, bool with_ctx, unsigned char* lds) {
;     ...
;                 for (int r = 0; r < 16; ++r) { S[r] = __builtin_amdgcn_exp2f(S[r]); ps += S[r]; }
;                 lrun += ps;
;                 u32x4 p0, p1;
;                 p0.x = pk2(S[0], S[1]); p0.y = pk2(S[2], S[3]); p0.z = pk2(S[4], S[5]); p0.w = pk2(S[6], S[7]);
;                 p1.x = pk2(S[8], S[9]); p1.y = pk2(S[10], S[11]); p1.z = pk2(S[12], S[13]); p1.w = pk2(S[14], S[15]);
;                 const bf16x8 pa0 = __builtin_bit_cast(bf16x8, p0), pa1 = __builtin_bit_cast(bf16x8, p1);
; #pragma unroll
;                 for (int j = 0; j < 4; ++j) O[j] = MFMA32(vf[2 * j], pa0, O[j]);
; #pragma unroll
;                 for (int j = 0; j < 4; ++j) O[j] = MFMA32(vf[2 * j + 1], pa1, O[j]);
;             }
;             if (t + 1 < nt) { unsigned char* kd = kdst + (cur ^ 1) * BUF; unsigned char* vd = vdst + (cur ^ 1) * BUF;
;                 *(u32x4*)kd = k0; *(u32x4*)(kd + 9216) = k1; *(u32x4*)vd = v0; *(u32x4*)(vd + 9216) = v1; }
;             __syncthreads();
.LBB0_412:
	v_exp_f32_e32 v67, v68
	v_exp_f32_e32 v68, v69
	v_exp_f32_e32 v69, v70
	v_exp_f32_e32 v70, v71
	v_exp_f32_e32 v71, v72
	v_exp_f32_e32 v72, v73
	v_exp_f32_e32 v73, v74
	v_exp_f32_e32 v74, v75
	v_cvt_pk_bf16_f32 v184, v67, v68
	v_cvt_pk_bf16_f32 v185, v69, v70
	v_cvt_pk_bf16_f32 v186, v71, v72
	v_cvt_pk_bf16_f32 v187, v73, v74
	v_exp_f32_e32 v75, v76
	v_exp_f32_e32 v76, v77
	s_waitcnt lgkmcnt(0)
	s_barrier
	v_mfma_f32_32x32x16_bf16 v[50:65], v[136:139], v[184:187], v[50:65]
	v_exp_f32_e32 v77, v78
	v_exp_f32_e32 v78, v79
	v_exp_f32_e32 v79, v80
	v_exp_f32_e32 v80, v81
	v_exp_f32_e32 v81, v82
	v_exp_f32_e32 v82, v83
	v_cvt_pk_bf16_f32 v214, v75, v76
	s_waitcnt lgkmcnt(9)
	v_mfma_f32_32x32x16_bf16 v[34:49], v[140:143], v[184:187], v[34:49]
	v_cvt_pk_bf16_f32 v215, v77, v78
	v_cvt_pk_bf16_f32 v216, v79, v80
	v_cvt_pk_bf16_f32 v217, v81, v82
	s_andn2_b64 vcc, exec, s[10:11]
	s_waitcnt lgkmcnt(7)
	v_mfma_f32_32x32x16_bf16 v[18:33], v[144:147], v[184:187], v[18:33]
	s_waitcnt lgkmcnt(5)
	v_mfma_f32_32x32x16_bf16 v[2:17], v[132:135], v[184:187], v[2:17]
	v_mfma_f32_32x32x16_bf16 v[50:65], v[116:119], v[214:217], v[50:65]
	v_mfma_f32_32x32x16_bf16 v[34:49], v[120:123], v[214:217], v[34:49]
	v_mfma_f32_32x32x16_bf16 v[18:33], v[124:127], v[214:217], v[18:33]
	s_waitcnt lgkmcnt(4)
	v_mfma_f32_32x32x16_bf16 v[2:17], v[128:131], v[214:217], v[2:17]
